# same as previous + rope-reuse guarded by grid size 256 (falls back to recomputing otherwise)
# baseline (speedup 1.0000x reference)
; __device__ __forceinline__ int tidx() { int t = threadIdx.x; asm volatile("" : "+v"(t)); return t; }
; __device__ __forceinline__ const float* kin(int i) { KArgs* k = (KArgs*)__builtin_amdgcn_kernarg_segment_ptr(); return *(const float* const volatile __attribute__((address_space(4)))*)&k->in[i]; }
; #define c opq(blockIdx.x)
; __device__ __forceinline__ void phase_prep0() {
;     const int tid = tidx(), lane = tid & 63, wid = tid >> 6, l7 = lane & 7; const int gw = blockIdx.x * 8 + wid, NGW = gridDim.x * 8;
;     const bf16_t* P = (const bf16_t*)(kws() + WS_P);
;     bf16_t* Q0 = (bf16_t*)((unsigned char*)kout() + DO_Q0); bf16_t* KALL = (bf16_t*)(kws() + WS_KALL); bf16_t* VALL = (bf16_t*)(kws() + WS_VALL);
;     bf16_t* XR = (bf16_t*)(kws() + WS_XR); bf16_t* XK = (bf16_t*)(kws() + WS_XK); bf16_t* XV = (bf16_t*)(kws() + WS_XV); bf16_t* KK = (bf16_t*)(kws() + WS_KK); bf16_t* AP = (bf16_t*)(kws() + WS_AP);
;     float muv[7][8], kkc[2][8], qn[8], kn[8];
;     { const float* mu = kin(9); const float* k_k = kin(19); const float* qnp = kin(24); const float* knp = kin(25);
; #pragma unroll
;       for (int p = 0; p < 7; ++p)
; #pragma unroll
;           for (int e = 0; e < 8; ++e) { const int c = p * 512 + lane * 8 + e; muv[p][e] = c < 3488 ? mu[c] : 0.f; }
; #pragma unroll
;       for (int p = 0; p < 2; ++p)
; #pragma unroll
;           for (int e = 0; e < 8; ++e) kkc[p][e] = k_k[p * 512 + lane * 8 + e];
; #pragma unroll
;       for (int e = 0; e < 8; ++e) { qn[e] = qnp[l7 * 8 + e]; kn[e] = knp[l7 * 8 + e]; } }
;     for (int row = gw; row < NT; row += NGW) {
;         const bf16_t* prow = P + (size_t)row * INP;
;         const bool isc = row >= NLAT; int b, t = 0, s = 0, grow = 0, gcol = 0;
;         if (!isc) { b = row >> 12; t = row & 4095; grow = t >> 6; gcol = t & 63; } else { b = (row - NLAT) >> 8; s = (row - NLAT) & 255; }
;         float cs[8], sn[8];
; #pragma unroll
;         for (int e = 0; e < 8; ++e) { cs[e] = 1.f; sn[e] = 0.f; }
;         if (!isc) {
; #pragma unroll
;             for (int e = 0; e < 8; ++e) { const int i = 8 * (l7 & 3) + e, mm = i & 15; const float pos = (float)(i < 16 ? grow : gcol); const float ang = pos * exp2f(-(float)mm * 0.8304820237218406f); cs[e] = cosf(ang); sn[e] = sinf(ang); } }
.LBB0_276:
	s_or_b64 exec, exec, s[30:31]
	v_ashrrev_i32_e32 v48, 6, v81
	v_readlane_b32 s0, v254, 2
	s_mul_hi_i32 s63, s78, 0x2800
	s_mul_i32 s62, s78, 0x2800
	v_add_u32_e32 v102, s0, v48
	s_movk_i32 s0, 0x4400
	v_cmp_gt_i32_e32 vcc, s0, v102
	s_and_saveexec_b64 s[2:3], vcc
	s_cbranch_execz .LBB0_499
	v_and_b32_e32 v82, 7, v81
	v_lshlrev_b32_e32 v76, 5, v82
	s_waitcnt vmcnt(11)
	v_mov_b32_e32 v83, v2
	s_waitcnt vmcnt(10)
	v_mov_b32_e32 v2, v6
	s_waitcnt vmcnt(9)
	v_mov_b32_e32 v6, v10
	s_waitcnt vmcnt(8)
	v_mov_b32_e32 v10, v14
	s_waitcnt vmcnt(6)
	v_mov_b32_e32 v14, v22
	v_mov_b32_e32 v22, v18
	s_waitcnt vmcnt(5)
	v_mov_b32_e32 v18, v26
	s_waitcnt vmcnt(4)
	v_mov_b32_e32 v26, v30
	s_waitcnt vmcnt(2)
	v_mov_b32_e32 v30, v38
	v_mov_b32_e32 v38, v34
	s_waitcnt vmcnt(0)
	v_mov_b32_e32 v34, v46
	v_mov_b32_e32 v46, v42
	v_lshlrev_b32_e32 v42, 2, v56
	global_load_dwordx4 v[48:51], v76, s[28:29] offset:16
	global_load_dwordx4 v[52:55], v76, s[28:29]
	global_load_dwordx4 v[56:59], v42, s[26:27] offset:2064
	global_load_dwordx4 v[60:63], v42, s[26:27] offset:2048
	global_load_dwordx4 v[64:67], v42, s[26:27] offset:16
	global_load_dwordx4 v[68:71], v42, s[26:27]
	global_load_dwordx4 v[72:75], v76, s[24:25] offset:16
	s_nop 0
	global_load_dwordx4 v[76:79], v76, s[24:25]
	v_lshlrev_b32_e32 v42, 3, v81
	v_bfe_u32 v143, v81, 3, 2
	v_and_b32_e32 v42, 8, v42
	v_and_b32_e32 v81, 2, v81
	v_cmp_eq_u32_e64 s[46:47], 0, v81
	v_cvt_f32_ubyte0_e32 v81, v42
	v_lshlrev_b32_e32 v100, 3, v82
	v_cmp_gt_u32_e64 s[38:39], 4, v82
	v_mul_f32_e32 v82, 0xbf549a78, v81
	s_mov_b32 s0, 0xc2fc0000
	v_cmp_gt_f32_e32 vcc, s0, v82
	v_mov_b32_e32 v82, 0x42800000
	v_not_b32_e32 v144, 63
	v_cndmask_b32_e32 v84, 0, v82, vcc
	v_fmac_f32_e32 v84, 0xbf549a78, v81
	v_exp_f32_e32 v81, v84
	v_cndmask_b32_e32 v84, 0, v144, vcc
	v_ashrrev_i32_e32 v103, 31, v102
	s_add_u32 s4, s4, 0x25c00000
	v_ldexp_f32 v145, v81, v84
	v_or_b32_e32 v81, 1, v42
	v_cvt_f32_ubyte0_e32 v81, v81
	v_mul_f32_e32 v84, 0xbf549a78, v81
	v_cmp_gt_f32_e32 vcc, s0, v84
	s_addc_u32 s5, s5, 0
	v_cmp_gt_u32_e64 s[40:41], 32, v80
	v_cndmask_b32_e32 v84, 0, v82, vcc
	v_fmac_f32_e32 v84, 0xbf549a78, v81
	v_exp_f32_e32 v81, v84
	v_cndmask_b32_e32 v84, 0, v144, vcc
	v_cmp_lt_u32_e64 s[42:43], 31, v80
	v_cmp_lt_u32_e64 s[44:45], 15, v80
	v_ldexp_f32 v146, v81, v84
	v_or_b32_e32 v81, 2, v42
	v_cvt_f32_ubyte0_e32 v81, v81
	v_mul_f32_e32 v84, 0xbf549a78, v81
	v_cmp_gt_f32_e32 vcc, s0, v84
	s_add_u32 s12, s12, 0x25300000
	s_addc_u32 s13, s13, 0
	v_cndmask_b32_e32 v84, 0, v82, vcc
	v_fmac_f32_e32 v84, 0xbf549a78, v81
	v_exp_f32_e32 v81, v84
	v_cndmask_b32_e32 v84, 0, v144, vcc
	v_mov_b32_e32 v105, 0
	s_ashr_i32 s79, s78, 31
	v_ldexp_f32 v147, v81, v84
	v_or_b32_e32 v81, 3, v42
	v_cvt_f32_ubyte0_e32 v81, v81
	v_mul_f32_e32 v84, 0xbf549a78, v81
	v_cmp_gt_f32_e32 vcc, s0, v84
	s_lshl_b64 s[64:65], s[78:79], 11
	s_lshl_b64 s[66:67], s[78:79], 10
	v_cndmask_b32_e32 v84, 0, v82, vcc
	v_fmac_f32_e32 v84, 0xbf549a78, v81
	v_exp_f32_e32 v81, v84
	v_cndmask_b32_e32 v84, 0, v144, vcc
	s_mov_b64 s[68:69], 0
	s_mov_b32 s6, 0xfe5163ab
	v_ldexp_f32 v148, v81, v84
	v_or_b32_e32 v81, 4, v42
	v_cvt_f32_ubyte0_e32 v81, v81
	v_mul_f32_e32 v84, 0xbf549a78, v81
	v_cmp_gt_f32_e32 vcc, s0, v84
	s_mov_b32 s7, 0x3c439041
	s_mov_b32 s24, 0xfc2757d1
	v_cndmask_b32_e32 v84, 0, v82, vcc
	v_fmac_f32_e32 v84, 0xbf549a78, v81
	v_exp_f32_e32 v81, v84
	v_cndmask_b32_e32 v84, 0, v144, vcc
	s_mov_b32 s25, 0x4e441529
	s_mov_b32 s26, 0xa2f9836e
	v_ldexp_f32 v149, v81, v84
	v_or_b32_e32 v81, 5, v42
	v_cvt_f32_ubyte0_e32 v81, v81
	v_mul_f32_e32 v84, 0xbf549a78, v81
	v_cmp_gt_f32_e32 vcc, s0, v84
	s_waitcnt vmcnt(4)
	v_mov_b32_e32 v106, v61
	v_mov_b32_e32 v61, v62
	v_cndmask_b32_e32 v84, 0, v82, vcc
	v_fmac_f32_e32 v84, 0xbf549a78, v81
	v_exp_f32_e32 v81, v84
	v_cndmask_b32_e32 v84, 0, v144, vcc
	v_mov_b32_e32 v62, v57
	v_mov_b32_e32 v57, v58
	v_ldexp_f32 v150, v81, v84
	v_or_b32_e32 v81, 6, v42
	v_cvt_f32_ubyte0_e32 v81, v81
	v_mul_f32_e32 v84, 0xbf549a78, v81
	v_cmp_gt_f32_e32 vcc, s0, v84
	v_or_b32_e32 v42, 7, v42
	v_cvt_f32_ubyte0_e32 v42, v42
	v_cndmask_b32_e32 v84, 0, v82, vcc
	v_fmac_f32_e32 v84, 0xbf549a78, v81
	v_exp_f32_e32 v81, v84
	v_cndmask_b32_e32 v84, 0, v144, vcc
	s_waitcnt vmcnt(2)
	v_mov_b32_e32 v58, v69
	v_mov_b32_e32 v69, v70
	v_ldexp_f32 v151, v81, v84
	v_mul_f32_e32 v81, 0xbf549a78, v42
	v_cmp_gt_f32_e32 vcc, s0, v81
	s_movk_i32 s0, 0xffeb
	v_mov_b32_e32 v70, v65
	v_cndmask_b32_e32 v81, 0, v82, vcc
	v_fmac_f32_e32 v81, 0xbf549a78, v42
	v_exp_f32_e32 v42, v81
	v_cndmask_b32_e32 v81, 0, v144, vcc
	v_mov_b32_e32 v65, v66
	v_lshlrev_b32_e32 v66, 4, v80
	v_ldexp_f32 v152, v42, v81
	v_subrev_u32_e32 v42, 52, v80
	v_cmp_lt_u32_e64 s[48:49], s0, v42
	v_mov_b32_e32 v42, v41
	v_mov_b32_e32 v41, v46
	v_mov_b32_e32 v46, v45
	v_mov_b32_e32 v45, v34
	v_mov_b32_e32 v34, v33
	v_mov_b32_e32 v33, v38
	v_mov_b32_e32 v38, v37
	v_mov_b32_e32 v37, v30
	v_mov_b32_e32 v30, v29
	v_mov_b32_e32 v29, v26
	v_mov_b32_e32 v26, v25
	v_mov_b32_e32 v25, v18
	v_mov_b32_e32 v18, v17
	v_mov_b32_e32 v17, v22
	v_mov_b32_e32 v22, v21
	v_mov_b32_e32 v21, v14
	v_mov_b32_e32 v14, v13
	v_mov_b32_e32 v13, v10
	v_mov_b32_e32 v10, v9
	v_mov_b32_e32 v9, v6
	v_mov_b32_e32 v6, v5
	v_mov_b32_e32 v5, v2
	v_mov_b32_e32 v2, v1
	v_mov_b32_e32 v1, v83
	v_lshlrev_b64 v[82:83], 10, v[102:103]
	v_lshlrev_b64 v[80:81], 11, v[102:103]
	v_lshl_add_u64 v[82:83], s[20:21], 0, v[82:83]
	s_mov_b64 s[0:1], 0x24200000
	v_lshl_add_u64 v[108:109], s[22:23], 0, v[80:81]
	v_lshl_add_u64 v[110:111], s[18:19], 0, v[80:81]
	v_lshl_add_u64 v[112:113], v[82:83], 0, s[0:1]
	v_lshl_add_u64 v[114:115], s[14:15], 0, v[80:81]
	v_lshl_add_u64 v[116:117], s[16:17], 0, v[80:81]
	v_lshl_add_u64 v[118:119], s[10:11], 0, v[80:81]
	s_movk_i32 s0, 0x2800
	v_mov_b64_e32 v[80:81], s[8:9]
	v_mad_i64_i32 v[120:121], s[0:1], v102, s0, v[80:81]
	v_mov_b32_e32 v107, v63
	v_mov_b32_e32 v63, v59
	v_mov_b32_e32 v59, v71
	v_mov_b32_e32 v71, v67
	v_mov_b32_e32 v67, v105
	s_brev_b32 s0, 18
	s_mov_b32 s1, 0x800000
	s_mov_b32 s22, 0xdb629599
	s_mov_b32 s23, 0xf534ddc0
	s_mov_b32 s27, 0x3fc90fda
	v_mov_b32_e32 v103, 0x3c0881c4
	v_mov_b32_e32 v153, 0xbab64f3b
	s_brev_b32 s28, 1
	s_mov_b32 s29, 0x7f800000
	s_mov_b32 s30, 0xffff0000
	v_mov_b32_e32 v154, 0x358637bd
	s_mov_b32 s70, 0x3e38aa3b
	s_movk_i32 s31, 0x7fff
	s_mov_b32 s33, 0x3f200000
	s_mov_b32 s34, 0x3fb8aa3b
	s_mov_b32 s35, 0xc2ce8ed0
	s_mov_b32 s36, 0x42b17218
	v_mov_b32_e32 v155, 0x3ca908c9
	s_brev_b32 s37, -2
	v_not_b32_e32 v156, 31
	v_mov_b32_e32 v157, 0x7fc00000
	v_mov_b32_e32 v158, 0x7f800000
	s_mov_b32 s98, 0
	s_cmpk_eq_i32 s76, 0x100
	s_cselect_b32 s99, 1, 0
	s_branch .LBB0_280

; __device__ __forceinline__ float red8(float x) { x += dppf<0xB1>(x); x += dppf<0x4E>(x); x += dppf<0x141>(x); return x; }
; __device__ __forceinline__ void phase_prep0() {
;     ...
;         for (int p = 0; p < 3; ++p) {
;             const u32x4 raw = *(const u32x4*)(prow + p * 512 + lane * 8); float x[8]; unpack8(raw, x);
;             float ss = 0.f;
; #pragma unroll
;             for (int e = 0; e < 8; ++e) ss += x[e] * x[e];
;             ss = red8(ss); const float rs = rsqrtf(ss * (1.f / 64.f) + 1e-6f);
;             float y[8];
; #pragma unroll
;             for (int e = 0; e < 8; ++e) y[e] = x[e] * rs * (p < 2 ? qn[e] : kn[e]);
;             if (!isc) {
; #pragma unroll
;                 for (int e = 0; e < 8; ++e) { const float o = __shfl_xor(y[e], 4); y[e] = (l7 < 4) ? y[e] * cs[e] - o * sn[e] : y[e] * cs[e] + o * sn[e]; } }
.LBB0_350:
	s_or_b64 exec, exec, s[14:15]
	s_add_u32 s98, s98, s99
	v_lshl_add_u64 v[122:123], v[120:121], 0, v[66:67]
	v_add_co_u32_e32 v80, vcc, 0x11000000, v122
	s_nop 1
	v_addc_co_u32_e32 v81, vcc, 0, v123, vcc
	global_load_dwordx4 v[80:83], v[80:81], off
	s_waitcnt vmcnt(0)
	v_lshlrev_b32_e32 v124, 16, v80
	v_and_b32_e32 v125, 0xffff0000, v80
	v_lshlrev_b32_e32 v80, 16, v81
	v_and_b32_e32 v81, 0xffff0000, v81
	v_pk_mul_f32 v[128:129], v[124:125], v[124:125]
	v_pk_mul_f32 v[130:131], v[80:81], v[80:81]
	v_add_f32_e32 v104, v128, v129
	v_lshlrev_b32_e32 v126, 16, v82
	v_and_b32_e32 v127, 0xffff0000, v82
	v_add_f32_e32 v104, v130, v104
	v_pk_mul_f32 v[132:133], v[126:127], v[126:127]
	v_add_f32_e32 v104, v131, v104
	v_lshlrev_b32_e32 v82, 16, v83
	v_and_b32_e32 v83, 0xffff0000, v83
	v_add_f32_e32 v104, v132, v104
	v_pk_mul_f32 v[134:135], v[82:83], v[82:83]
	v_add_f32_e32 v104, v133, v104
	v_add_f32_e32 v104, v134, v104
	v_add_f32_e32 v104, v135, v104
	s_nop 1
	v_add_f32_dpp v104, v104, v104 quad_perm:[1,0,3,2] row_mask:0xf bank_mask:0xf bound_ctrl:1
	s_nop 1
	v_add_f32_dpp v104, v104, v104 quad_perm:[2,3,0,1] row_mask:0xf bank_mask:0xf bound_ctrl:1
	s_nop 1
	v_add_f32_dpp v104, v104, v104 row_half_mirror row_mask:0xf bank_mask:0xf bound_ctrl:1
	v_fmamk_f32 v104, v104, 0x3c800000, v154
	v_mul_f32_e32 v128, 0x4b800000, v104
	v_cmp_gt_f32_e32 vcc, s1, v104
	s_nop 1
	v_cndmask_b32_e32 v104, v104, v128, vcc
	v_rsq_f32_e32 v128, v104
	v_mbcnt_hi_u32_b32 v104, -1, v220
	v_mul_f32_e32 v129, 0x45800000, v128
	v_cndmask_b32_e32 v128, v128, v129, vcc
	v_pk_mul_f32 v[124:125], v[128:129], v[124:125] op_sel_hi:[0,1]
	v_pk_mul_f32 v[130:131], v[128:129], v[80:81] op_sel_hi:[0,1]
	v_pk_mul_f32 v[126:127], v[128:129], v[126:127] op_sel_hi:[0,1]
	v_pk_mul_f32 v[128:129], v[128:129], v[82:83] op_sel_hi:[0,1]
	v_pk_mul_f32 v[80:81], v[52:53], v[124:125]
	v_pk_mul_f32 v[82:83], v[54:55], v[130:131]
	v_pk_mul_f32 v[124:125], v[48:49], v[126:127]
	v_pk_mul_f32 v[126:127], v[50:51], v[128:129]
	v_mov_b32_e32 v130, v80
	v_mov_b32_e32 v132, v81
	v_mov_b32_e32 v131, v82
	v_mov_b32_e32 v133, v83
	v_mov_b32_e32 v128, v124
	v_mov_b32_e32 v134, v125
	v_mov_b32_e32 v129, v126
	v_mov_b32_e32 v135, v127
	s_and_saveexec_b64 s[8:9], s[50:51]
	s_cbranch_execz .LBB0_352
	v_and_b32_e32 v129, 64, v104
	v_xor_b32_e32 v128, 4, v104
	v_add_u32_e32 v129, 64, v129
	v_cmp_lt_i32_e32 vcc, v128, v129
	s_nop 1
	v_cndmask_b32_e32 v128, v104, v128, vcc
	v_lshlrev_b32_e32 v135, 2, v128
	ds_bpermute_b32 v128, v135, v80
	ds_bpermute_b32 v129, v135, v81
	ds_bpermute_b32 v130, v135, v82
	ds_bpermute_b32 v131, v135, v83
	ds_bpermute_b32 v132, v135, v124
	ds_bpermute_b32 v133, v135, v125
	ds_bpermute_b32 v134, v135, v126
	ds_bpermute_b32 v135, v135, v127
	s_waitcnt lgkmcnt(6)
	v_pk_mul_f32 v[128:129], v[98:99], v[128:129]
	s_waitcnt lgkmcnt(4)
	v_pk_mul_f32 v[130:131], v[94:95], v[130:131]
	s_waitcnt lgkmcnt(2)
	v_pk_mul_f32 v[132:133], v[90:91], v[132:133]
	v_cndmask_b32_e64 v165, v129, -v129, s[38:39]
	s_waitcnt lgkmcnt(0)
	v_pk_mul_f32 v[134:135], v[86:87], v[134:135]
	v_cndmask_b32_e64 v164, v128, -v128, s[38:39]
	v_cndmask_b32_e64 v131, v131, -v131, s[38:39]
	v_cndmask_b32_e64 v130, v130, -v130, s[38:39]
	v_cndmask_b32_e64 v129, v133, -v133, s[38:39]
	v_cndmask_b32_e64 v128, v132, -v132, s[38:39]
	v_cndmask_b32_e64 v133, v135, -v135, s[38:39]
	v_cndmask_b32_e64 v132, v134, -v134, s[38:39]
	v_pk_fma_f32 v[126:127], v[84:85], v[126:127], v[132:133]
	v_pk_fma_f32 v[128:129], v[88:89], v[124:125], v[128:129]
	v_pk_fma_f32 v[82:83], v[92:93], v[82:83], v[130:131]
	v_pk_fma_f32 v[130:131], v[96:97], v[80:81], v[164:165]
	v_mov_b32_e32 v133, v83
	v_mov_b32_e32 v132, v131
	v_mov_b32_e32 v131, v82
	v_mov_b32_e32 v134, v129
	v_mov_b32_e32 v129, v126
	v_mov_b32_e32 v135, v127
